# w_ff2 weight conversion deferred to retention entry for batches 0,1 (2 tiles each); front pass 2 = wrc,w_o,w1 split 0/1/3/3
# speedup vs baseline: 1.0038x; 1.0038x over previous
.LBB0_34:
	s_cmp_lg_u32 s100, 0
	s_cbranch_scc1 .Lp0_go
	s_lshr_b32 s0, s83, 6
	s_and_b32 s1, s83, 63
	s_movk_i32 s4, 0
	s_movk_i32 s5, 0
	s_cmp_eq_u32 s0, 1
	s_cselect_b32 s4, 2, s4
	s_cselect_b32 s5, 0, s5
	s_cmp_eq_u32 s0, 2
	s_cselect_b32 s4, 3, s4
	s_cselect_b32 s5, 128, s5
	s_cmp_eq_u32 s0, 3
	s_cselect_b32 s4, 3, s4
	s_cselect_b32 s5, 320, s5
	s_mul_i32 s6, s1, s4
	s_add_i32 s8, s5, s6
	s_add_i32 s10, s8, s4
	v_writelane_b32 v252, s9, 0
	v_writelane_b32 v252, s48, 1
	v_writelane_b32 v252, s49, 2
	v_writelane_b32 v252, s54, 3
	v_writelane_b32 v252, s55, 4
	v_writelane_b32 v252, s65, 5
	v_writelane_b32 v252, s68, 6
	v_writelane_b32 v252, s84, 7
	v_writelane_b32 v252, s85, 8
	v_writelane_b32 v252, s86, 9
	v_writelane_b32 v252, s87, 10
	v_mov_b32_e32 v253, v88
	v_mov_b32_e32 v254, v90
	v_mov_b32_e32 v255, v91

.LBB0_152:
	s_waitcnt vmcnt(0)
	v_cmp_eq_u32_e32 vcc, 0, v90
	s_waitcnt vmcnt(0)
	s_barrier
	s_cmp_eq_u32 s100, 2
	s_cbranch_scc1 .Lp0_third_back
	s_cmp_lg_u32 s100, 0
	s_cbranch_scc1 .Lp0_second_done
	s_and_saveexec_b64 s[0:1], vcc
	s_cbranch_execz .LBB0_155
	s_mov_b64 s[4:5], exec
	v_mbcnt_lo_u32_b32 v0, s4, 0
	v_mbcnt_hi_u32_b32 v0, s5, v0
	v_cmp_eq_u32_e32 vcc, 0, v0
	s_and_b64 s[6:7], exec, vcc
	s_mov_b64 exec, s[6:7]
	s_cbranch_execz .LBB0_155
	s_bcnt1_i32_b64 s3, s[4:5]
	v_mov_b32_e32 v0, 0x8000
	v_mov_b32_e32 v1, s3
	global_atomic_add v0, v1, s[54:55] offset:512
.LBB0_155:
	s_or_b64 exec, exec, s[0:1]
	s_mov_b32 s100, 1
	s_lshr_b32 s0, s83, 6
	s_and_b32 s1, s83, 63
	s_movk_i32 s4, 0
	s_movk_i32 s5, 512
	s_cmp_eq_u32 s0, 1
	s_cselect_b32 s4, 1, s4
	s_cselect_b32 s5, 512, s5
	s_cmp_eq_u32 s0, 2
	s_cselect_b32 s4, 3, s4
	s_cselect_b32 s5, 576, s5
	s_cmp_eq_u32 s0, 3
	s_cselect_b32 s4, 3, s4
	s_cselect_b32 s5, 768, s5
	s_mul_i32 s6, s1, s4
	s_add_i32 s8, s5, s6
	s_add_i32 s10, s8, s4
	s_cmp_eq_u32 s4, 0
	s_cbranch_scc1 .Lp0_second_done
	s_mul_i32 s3, s62, 0x2080
	s_mov_b32 s33, s3
	s_branch .LBB0_34

.LBB0_292:
	s_cmp_lt_i32 s68, 4
	s_cselect_b64 s[0:1], -1, 0
	s_cmp_gt_i32 s69, 3
	s_cselect_b64 s[4:5], -1, 0
	s_and_b64 s[0:1], s[0:1], s[4:5]
	s_andn2_b64 vcc, exec, s[0:1]
	s_cbranch_vccnz .LBB0_435
	s_lshr_b32 s0, s83, 6
	s_and_b32 s1, s83, 63
	s_movk_i32 s4, 2
	s_movk_i32 s5, 960
	s_cmp_eq_u32 s0, 1
	s_cselect_b32 s4, 2, s4
	s_cselect_b32 s5, 1088, s5
	s_cmp_eq_u32 s0, 2
	s_cselect_b32 s4, 0, s4
	s_cselect_b32 s5, 1216, s5
	s_cmp_eq_u32 s0, 3
	s_cselect_b32 s4, 0, s4
	s_cselect_b32 s5, 1216, s5
	s_mul_i32 s6, s1, s4
	s_add_i32 s8, s5, s6
	s_add_i32 s10, s8, s4
	s_cmp_eq_u32 s4, 0
	s_cbranch_scc1 .Lp0_third_done
	v_writelane_b32 v252, s26, 20
	v_writelane_b32 v252, s3, 21
	v_writelane_b32 v252, s54, 22
	v_writelane_b32 v252, s55, 23
	s_nop 1
	v_readlane_b32 s9, v252, 0
	v_readlane_b32 s48, v252, 1
	v_readlane_b32 s49, v252, 2
	v_readlane_b32 s54, v252, 3
	v_readlane_b32 s55, v252, 4
	v_readlane_b32 s65, v252, 5
	v_readlane_b32 s68, v252, 6
	v_readlane_b32 s84, v252, 7
	v_readlane_b32 s85, v252, 8
	v_readlane_b32 s86, v252, 9
	v_readlane_b32 s87, v252, 10
	v_mov_b32_e32 v88, v253
	v_mov_b32_e32 v90, v254
	v_mov_b32_e32 v91, v255
	v_mov_b32_e32 v253, v21
	v_mbcnt_lo_u32_b32 v92, -1, 0
	v_mbcnt_hi_u32_b32 v92, -1, v92
	s_mov_b32 s100, 2
	s_mul_i32 s3, s62, 0x2080
	s_mov_b32 s33, s3
	s_branch .LBB0_34
.Lp0_third_back:
	v_readlane_b32 s26, v252, 20
	v_readlane_b32 s3, v252, 21
	v_readlane_b32 s54, v252, 22
	v_readlane_b32 s55, v252, 23
	v_mov_b32_e32 v21, v253
	s_nop 1
.Lp0_third_done:
	s_add_u32 s30, s54, 0x4200
	s_addc_u32 s31, s55, 0
	v_readlane_b32 s0, v251, 20
	s_add_u32 s12, s54, 0x20000
	v_readlane_b32 s1, v251, 21
	s_addc_u32 s63, s55, 0
	s_lshl_b32 s13, s0, 6
	v_readlane_b32 s0, v251, 0
	s_waitcnt vmcnt(0)
	v_readlane_b32 s1, v251, 1
	s_andn2_b64 vcc, exec, s[0:1]
	s_waitcnt vmcnt(0)
	v_cndmask_b32_e64 v0, 0, 1, s[0:1]
	v_cmp_ne_u32_e64 s[70:71], 1, v0
	s_barrier
	s_cbranch_vccnz .LBB0_318
	v_mbcnt_lo_u32_b32 v0, -1, 0
	v_mbcnt_hi_u32_b32 v0, -1, v0
	s_nop 0
	v_cmp_eq_u32_e32 vcc, 0, v0
	s_and_saveexec_b64 s[4:5], vcc
	s_cbranch_execz .LBB0_317
	v_readlane_b32 s0, v251, 24
	v_readlane_b32 s1, v251, 25
	s_andn2_b64 vcc, exec, s[0:1]
	s_cbranch_vccnz .LBB0_297
	buffer_wbl2 sc1
